# v051 + wave-major item numbering (balances weight-copy items across CUs in P0 and in every seam)
# speedup vs baseline: 1.0135x; 1.0135x over previous
; __global__ void __launch_bounds__(NWAVES * 64, 2) hybrid_fwd(Args args) {
;     ...
;         const int gw = vcu * NWAVES + wave, NGW = G * NWAVES;
;         constexpr int I_IN = (D / 64) * (PW / 64), I_OUT = (D / 64) * (D / 64), I_UP = (D / 64) * (FF / 64), I_DN = (FF / 64) * (D / 64), I_L = I_IN + I_OUT + I_UP + I_DN;
;         const float* const w_in = args.in[z + 1]; const float* const w_out = args.in[z + 2]; const float* const w_up = args.in[z + 13]; const float* const w_dn = args.in[z + 14];
;         const float* const g_attn = args.in[z + 11]; const float* const g_mlp = args.in[z + 12];
;         auto decode = [&](int it) -> TItem {
;             const int l = it / I_L; int r = it % I_L; TItem d;
;             const float* W; bf16* WT; const float* g = nullptr; int K = D, N = D, perm = 0;
;             if (r < I_IN) { W = w_in + (size_t)l * D * PW; WT = (bf16*)(ws + WS_WIN) + (size_t)l * PW * D; N = PW; g = g_attn + l * D; perm = 1; }
;             else if ((r -= I_IN) < I_OUT) { W = w_out + (size_t)l * D * D; WT = (bf16*)(ws + WS_WOUT) + (size_t)l * D * D; }
;             else if ((r -= I_OUT) < I_UP) { W = w_up + (size_t)l * D * FF; WT = (bf16*)(ws + WS_WUP) + (size_t)l * FF * D; N = FF; g = g_mlp + l * D; }
;             else { r -= I_UP; W = w_dn + (size_t)l * FF * D; WT = (bf16*)(ws + WS_WDN) + (size_t)l * D * FF; K = FF; }
;             const int nblk = N / 64, k0 = 64 * (r / nblk), n0 = 64 * (r % nblk);
;             d.src = W + (size_t)k0 * N + n0; d.g = g ? g + k0 : nullptr; d.dst = WT + (size_t)(k0 >> 6) * (256 * 64); d.N = N; d.K = K; d.perm = perm | (n0 << 1);
;             return d; };
;         {
;             int it = gw; f32x4 va[16]; float ga[16]; TItem d0;
;             if (it < DEPTH * I_L) { d0 = decode(it); titem_load(d0, va, ga, lane); }
.Lcv_entry:
	s_load_dwordx2 s[4:5], s[84:85], 0x90
	v_and_b32_e32 v177, 63, v169
	s_waitcnt lgkmcnt(0)
	s_cmp_lt_i32 s4, 1
	s_cselect_b64 s[0:1], -1, 0
	s_cmp_gt_i32 s5, 0
	s_cselect_b64 s[4:5], -1, 0
	s_and_b64 s[0:1], s[0:1], s[4:5]
	s_andn2_b64 vcc, exec, s[0:1]
	s_cbranch_vccnz .LBB0_154
	v_readlane_b32 s1, v254, 0
	s_lshr_b32 s0, s3, 6
	s_mul_i32 s0, s0, s88
	s_add_i32 s22, s1, s0
	s_add_i32 s22, s22, s100
	s_cmp_lt_i32 s22, s99
	s_mov_b32 s0, 0
	s_cselect_b64 s[26:27], -1, 0
	s_ashr_i32 s1, s0, 31
	s_lshl_b64 s[0:1], s[0:1], 3
	s_add_u32 s6, s84, s0
	s_addc_u32 s7, s85, s1
	s_load_dwordx2 s[24:25], s[6:7], 0x88
	s_load_dwordx4 s[16:19], s[6:7], 0x8
	s_load_dwordx8 s[8:15], s[6:7], 0x58
	v_bfe_u32 v2, v169, 1, 5
	v_and_b32_e32 v144, 24, v2
	v_lshlrev_b32_e32 v1, 2, v169
	v_or_b32_e32 v145, 1, v144
	v_or_b32_e32 v146, 2, v144
	v_or_b32_e32 v147, 3, v144
	v_or_b32_e32 v148, 4, v144
	v_or_b32_e32 v149, 5, v144
	v_or_b32_e32 v150, 6, v144
	v_or_b32_e32 v151, 32, v144
	v_or_b32_e32 v152, 33, v144
	v_or_b32_e32 v153, 34, v144
	v_or_b32_e32 v154, 35, v144
	v_or_b32_e32 v155, 36, v144
	v_or_b32_e32 v156, 37, v144
	v_or_b32_e32 v157, 38, v144
	v_and_b32_e32 v158, 60, v1
	v_mov_b32_e32 v176, 0
	v_or_b32_e32 v159, 7, v2
	s_cmp_ge_i32 s22, s99
	v_or_b32_e32 v160, 39, v2
	s_cbranch_scc1 .LBB0_13
	s_mul_hi_i32 s0, s22, 0x2aaaaaab
	s_lshr_b32 s1, s0, 31
	s_ashr_i32 s0, s0, 11
	s_add_i32 s30, s0, s1
	s_mul_i32 s0, s30, 0x3000
	s_lshl_b32 s28, s30, 11
	s_sub_i32 s42, s22, s0
	s_ashr_i32 s31, s30, 31
	s_ashr_i32 s29, s28, 31
	s_cmpk_gt_i32 s42, 0xbff
	s_cbranch_scc0 .LBB0_14
	v_mov_b32_e32 v2, 0x1000
	v_sub_co_u32_e32 v2, vcc, s42, v2
	s_andn2_b64 vcc, exec, vcc
	v_readfirstlane_b32 s43, v2
	s_cbranch_vccz .LBB0_15
	v_mov_b32_e32 v2, 0x2000
	v_sub_co_u32_e32 v2, vcc, s42, v2
	s_movk_i32 s3, 0x2000
	v_readfirstlane_b32 s23, v2
	s_lshl_b64 s[38:39], s[30:31], 26
	s_andn2_b64 vcc, exec, vcc
	s_lshl_b64 s[40:41], s[30:31], 25
	s_cbranch_vccz .LBB0_16
	s_waitcnt lgkmcnt(0)
	s_add_u32 s4, s14, s38
	s_addc_u32 s5, s15, s39
	s_add_u32 s0, s24, s40
	s_addc_u32 s1, s25, s41
	s_add_u32 s0, s0, 0x10200000
	s_addc_u32 s1, s1, 0
	s_mov_b64 s[36:37], 0
	s_mov_b32 s43, s23
	s_branch .LBB0_17

.LBB0_153:
	s_or_b64 exec, exec, s[0:1]
	v_readfirstlane_b32 s101, v169
	s_nop 3
	s_lshr_b32 s101, s101, 6
	s_cmp_eq_u32 s101, 0
	s_cbranch_scc1 .Lcv_skip_Z
	s_mov_b32 s100, 0
	s_cmp_gt_u32 s100, 18
	s_cbranch_scc1 .Lcv_skip_Z
	s_mul_i32 s100, s100, 2458
	s_add_i32 s100, s100, 3072
	s_add_i32 s99, s100, 2458
	s_min_i32 s99, s99, 0xc000
	s_sub_i32 s100, s100, s88
	s_mov_b32 s98, 7
	s_mov_b32 s101, 6
	v_readfirstlane_b32 s3, v169
	s_branch .Lcv_entry

; __device__ __forceinline__ unsigned xb_ld(unsigned* p)              { return __hip_atomic_load(p, __ATOMIC_RELAXED, __HIP_MEMORY_SCOPE_AGENT); }
; __device__ __forceinline__ unsigned xb_add(unsigned* p, unsigned v) { return __hip_atomic_fetch_add(p, v, __ATOMIC_RELAXED, __HIP_MEMORY_SCOPE_AGENT); }
; #define XB_SPIN(cond, bar) do { unsigned _sp = 0; while (cond) { __builtin_amdgcn_s_sleep(1); \
;     if ((++_sp & 255u) == 0u) { if (xb_ld(&(bar)[XB_TMO])) break; if (_sp > XB_SPIN_CAP) { atomicAdd(&(bar)[XB_TMO], 1u); break; } } } } while (0)
; __device__ __forceinline__ void xcd_barrier(const XcdBarrier& b) {
;     asm volatile("s_waitcnt vmcnt(0)" ::: "memory");
;     __syncthreads();
;     if (threadIdx.x == 0) {
;         unsigned* bar = b.bar;
;         __builtin_amdgcn_s_waitcnt(0);
;         unsigned nloc = b.st[0], nx = b.st[1];
;         if (nloc == 0u) { xcd_barrier_complete(bar, b.x, nloc, nx); b.st[0] = nloc; b.st[1] = nx; }
;         const unsigned old = xb_add(&bar[XB_XSUB(b.x)], 1u);
;         const unsigned gen = old / nloc;
;         if (old + 1u == (gen + 1u) * nloc) {
;             __builtin_amdgcn_fence(__ATOMIC_RELEASE, "agent");
;             asm volatile("s_waitcnt vmcnt(0)" ::: "memory");
;             const unsigned og = xb_add(&bar[XB_TOP], 1u);
;             const unsigned tg = og / nx;
;             if (og + 1u == (tg + 1u) * nx) xb_add(&bar[XB_TOPGEN], 1u);
;             else XB_SPIN(xb_ld(&bar[XB_TOPGEN]) == tg, bar);
;             __builtin_amdgcn_fence(__ATOMIC_ACQUIRE, "agent");
;             xb_add(&bar[XB_XGEN(b.x)], 1u);
;             asm volatile("s_waitcnt vmcnt(0)" ::: "memory");
;         } else {
;             XB_SPIN(xb_ld(&bar[XB_XGEN(b.x)]) == gen, bar);
;             __builtin_amdgcn_fence(__ATOMIC_ACQUIRE, "agent");
;             asm volatile("s_waitcnt vmcnt(0)" ::: "memory");
;         }
;     }
;     __syncthreads();
; }
.LBB0_156:
	s_or_b64 exec, exec, s[0:1]
	v_readfirstlane_b32 s101, v169
	s_nop 3
	s_lshr_b32 s101, s101, 6
	s_cmp_eq_u32 s101, 0
	s_cbranch_scc1 .Lcv_skip_E
	v_readlane_b32 s100, v255, 44
	s_nop 3
	s_mul_i32 s100, s100, 5
	s_add_i32 s100, s100, 5
	s_cmp_gt_u32 s100, 18
	s_cbranch_scc1 .Lcv_skip_E
	s_mul_i32 s100, s100, 2458
	s_add_i32 s100, s100, 3072
	s_add_i32 s99, s100, 2458
	s_min_i32 s99, s99, 0xc000
	s_sub_i32 s100, s100, s88
	s_mov_b32 s98, 7
	s_mov_b32 s101, 5
	v_readfirstlane_b32 s3, v169
	s_branch .Lcv_entry

; __device__ __forceinline__ unsigned xb_ld(unsigned* p)              { return __hip_atomic_load(p, __ATOMIC_RELAXED, __HIP_MEMORY_SCOPE_AGENT); }
; __device__ __forceinline__ unsigned xb_add(unsigned* p, unsigned v) { return __hip_atomic_fetch_add(p, v, __ATOMIC_RELAXED, __HIP_MEMORY_SCOPE_AGENT); }
; #define XB_SPIN(cond, bar) do { unsigned _sp = 0; while (cond) { __builtin_amdgcn_s_sleep(1); \
;     if ((++_sp & 255u) == 0u) { if (xb_ld(&(bar)[XB_TMO])) break; if (_sp > XB_SPIN_CAP) { atomicAdd(&(bar)[XB_TMO], 1u); break; } } } } while (0)
; __device__ __forceinline__ void xcd_barrier(const XcdBarrier& b) {
;     asm volatile("s_waitcnt vmcnt(0)" ::: "memory");
;     __syncthreads();
;     if (threadIdx.x == 0) {
;         unsigned* bar = b.bar;
;         __builtin_amdgcn_s_waitcnt(0);
;         unsigned nloc = b.st[0], nx = b.st[1];
;         if (nloc == 0u) { xcd_barrier_complete(bar, b.x, nloc, nx); b.st[0] = nloc; b.st[1] = nx; }
;         const unsigned old = xb_add(&bar[XB_XSUB(b.x)], 1u);
;         const unsigned gen = old / nloc;
;         if (old + 1u == (gen + 1u) * nloc) {
;             __builtin_amdgcn_fence(__ATOMIC_RELEASE, "agent");
;             asm volatile("s_waitcnt vmcnt(0)" ::: "memory");
;             const unsigned og = xb_add(&bar[XB_TOP], 1u);
;             const unsigned tg = og / nx;
;             if (og + 1u == (tg + 1u) * nx) xb_add(&bar[XB_TOPGEN], 1u);
;             else XB_SPIN(xb_ld(&bar[XB_TOPGEN]) == tg, bar);
;             __builtin_amdgcn_fence(__ATOMIC_ACQUIRE, "agent");
;             xb_add(&bar[XB_XGEN(b.x)], 1u);
;             asm volatile("s_waitcnt vmcnt(0)" ::: "memory");
;         } else {
;             XB_SPIN(xb_ld(&bar[XB_XGEN(b.x)]) == gen, bar);
;             __builtin_amdgcn_fence(__ATOMIC_ACQUIRE, "agent");
;             asm volatile("s_waitcnt vmcnt(0)" ::: "memory");
;         }
;     }
;     __syncthreads();
; }
.LBB0_292:
	s_or_b64 exec, exec, s[0:1]
	v_readfirstlane_b32 s101, v169
	s_nop 3
	s_lshr_b32 s101, s101, 6
	s_cmp_eq_u32 s101, 0
	s_cbranch_scc1 .Lcv_skip_A
	v_readlane_b32 s100, v255, 44
	s_nop 3
	s_mul_i32 s100, s100, 5
	s_add_i32 s100, s100, 1
	s_cmp_gt_u32 s100, 18
	s_cbranch_scc1 .Lcv_skip_A
	s_mul_i32 s100, s100, 2458
	s_add_i32 s100, s100, 3072
	s_add_i32 s99, s100, 2458
	s_min_i32 s99, s99, 0xc000
	s_sub_i32 s100, s100, s88
	s_mov_b32 s98, 7
	s_mov_b32 s101, 1
	v_readfirstlane_b32 s3, v169
	s_branch .Lcv_entry

; __device__ __forceinline__ unsigned xb_ld(unsigned* p)              { return __hip_atomic_load(p, __ATOMIC_RELAXED, __HIP_MEMORY_SCOPE_AGENT); }
; __device__ __forceinline__ unsigned xb_add(unsigned* p, unsigned v) { return __hip_atomic_fetch_add(p, v, __ATOMIC_RELAXED, __HIP_MEMORY_SCOPE_AGENT); }
; #define XB_SPIN(cond, bar) do { unsigned _sp = 0; while (cond) { __builtin_amdgcn_s_sleep(1); \
;     if ((++_sp & 255u) == 0u) { if (xb_ld(&(bar)[XB_TMO])) break; if (_sp > XB_SPIN_CAP) { atomicAdd(&(bar)[XB_TMO], 1u); break; } } } } while (0)
; __device__ __forceinline__ void xcd_barrier(const XcdBarrier& b) {
;     asm volatile("s_waitcnt vmcnt(0)" ::: "memory");
;     __syncthreads();
;     if (threadIdx.x == 0) {
;         unsigned* bar = b.bar;
;         __builtin_amdgcn_s_waitcnt(0);
;         unsigned nloc = b.st[0], nx = b.st[1];
;         if (nloc == 0u) { xcd_barrier_complete(bar, b.x, nloc, nx); b.st[0] = nloc; b.st[1] = nx; }
;         const unsigned old = xb_add(&bar[XB_XSUB(b.x)], 1u);
;         const unsigned gen = old / nloc;
;         if (old + 1u == (gen + 1u) * nloc) {
;             __builtin_amdgcn_fence(__ATOMIC_RELEASE, "agent");
;             asm volatile("s_waitcnt vmcnt(0)" ::: "memory");
;             const unsigned og = xb_add(&bar[XB_TOP], 1u);
;             const unsigned tg = og / nx;
;             if (og + 1u == (tg + 1u) * nx) xb_add(&bar[XB_TOPGEN], 1u);
;             else XB_SPIN(xb_ld(&bar[XB_TOPGEN]) == tg, bar);
;             __builtin_amdgcn_fence(__ATOMIC_ACQUIRE, "agent");
;             xb_add(&bar[XB_XGEN(b.x)], 1u);
;             asm volatile("s_waitcnt vmcnt(0)" ::: "memory");
;         } else {
;             XB_SPIN(xb_ld(&bar[XB_XGEN(b.x)]) == gen, bar);
;             __builtin_amdgcn_fence(__ATOMIC_ACQUIRE, "agent");
;             asm volatile("s_waitcnt vmcnt(0)" ::: "memory");
;         }
;     }
;     __syncthreads();
; }
.LBB0_435:
	s_or_b64 exec, exec, s[0:1]
	v_readfirstlane_b32 s101, v169
	s_nop 3
	s_lshr_b32 s101, s101, 6
	s_cmp_eq_u32 s101, 0
	s_cbranch_scc1 .Lcv_skip_B
	v_readlane_b32 s100, v255, 44
	s_nop 3
	s_mul_i32 s100, s100, 5
	s_add_i32 s100, s100, 2
	s_cmp_gt_u32 s100, 18
	s_cbranch_scc1 .Lcv_skip_B
	s_mul_i32 s100, s100, 2458
	s_add_i32 s100, s100, 3072
	s_add_i32 s99, s100, 2458
	s_min_i32 s99, s99, 0xc000
	s_sub_i32 s100, s100, s88
	s_mov_b32 s98, 7
	s_mov_b32 s101, 2
	v_readfirstlane_b32 s3, v169
	s_branch .Lcv_entry

; __device__ __forceinline__ unsigned xb_ld(unsigned* p)              { return __hip_atomic_load(p, __ATOMIC_RELAXED, __HIP_MEMORY_SCOPE_AGENT); }
; __device__ __forceinline__ unsigned xb_add(unsigned* p, unsigned v) { return __hip_atomic_fetch_add(p, v, __ATOMIC_RELAXED, __HIP_MEMORY_SCOPE_AGENT); }
; #define XB_SPIN(cond, bar) do { unsigned _sp = 0; while (cond) { __builtin_amdgcn_s_sleep(1); \
;     if ((++_sp & 255u) == 0u) { if (xb_ld(&(bar)[XB_TMO])) break; if (_sp > XB_SPIN_CAP) { atomicAdd(&(bar)[XB_TMO], 1u); break; } } } } while (0)
; __device__ __forceinline__ void xcd_barrier(const XcdBarrier& b) {
;     asm volatile("s_waitcnt vmcnt(0)" ::: "memory");
;     __syncthreads();
;     if (threadIdx.x == 0) {
;         unsigned* bar = b.bar;
;         __builtin_amdgcn_s_waitcnt(0);
;         unsigned nloc = b.st[0], nx = b.st[1];
;         if (nloc == 0u) { xcd_barrier_complete(bar, b.x, nloc, nx); b.st[0] = nloc; b.st[1] = nx; }
;         const unsigned old = xb_add(&bar[XB_XSUB(b.x)], 1u);
;         const unsigned gen = old / nloc;
;         if (old + 1u == (gen + 1u) * nloc) {
;             __builtin_amdgcn_fence(__ATOMIC_RELEASE, "agent");
;             asm volatile("s_waitcnt vmcnt(0)" ::: "memory");
;             const unsigned og = xb_add(&bar[XB_TOP], 1u);
;             const unsigned tg = og / nx;
;             if (og + 1u == (tg + 1u) * nx) xb_add(&bar[XB_TOPGEN], 1u);
;             else XB_SPIN(xb_ld(&bar[XB_TOPGEN]) == tg, bar);
;             __builtin_amdgcn_fence(__ATOMIC_ACQUIRE, "agent");
;             xb_add(&bar[XB_XGEN(b.x)], 1u);
;             asm volatile("s_waitcnt vmcnt(0)" ::: "memory");
;         } else {
;             XB_SPIN(xb_ld(&bar[XB_XGEN(b.x)]) == gen, bar);
;             __builtin_amdgcn_fence(__ATOMIC_ACQUIRE, "agent");
;             asm volatile("s_waitcnt vmcnt(0)" ::: "memory");
;         }
;     }
;     __syncthreads();
; }
.LBB0_536:
	s_or_b64 exec, exec, s[0:1]
	v_readfirstlane_b32 s101, v169
	s_nop 3
	s_lshr_b32 s101, s101, 6
	s_cmp_eq_u32 s101, 0
	s_cbranch_scc1 .Lcv_skip_C
	v_readlane_b32 s100, v255, 44
	s_nop 3
	s_mul_i32 s100, s100, 5
	s_add_i32 s100, s100, 3
	s_cmp_gt_u32 s100, 18
	s_cbranch_scc1 .Lcv_skip_C
	s_mul_i32 s100, s100, 2458
	s_add_i32 s100, s100, 3072
	s_add_i32 s99, s100, 2458
	s_min_i32 s99, s99, 0xc000
	s_sub_i32 s100, s100, s88
	s_mov_b32 s98, 7
	s_mov_b32 s101, 3
	v_readfirstlane_b32 s3, v169
	s_branch .Lcv_entry

; __device__ __forceinline__ unsigned xb_ld(unsigned* p)              { return __hip_atomic_load(p, __ATOMIC_RELAXED, __HIP_MEMORY_SCOPE_AGENT); }
; __device__ __forceinline__ unsigned xb_add(unsigned* p, unsigned v) { return __hip_atomic_fetch_add(p, v, __ATOMIC_RELAXED, __HIP_MEMORY_SCOPE_AGENT); }
; #define XB_SPIN(cond, bar) do { unsigned _sp = 0; while (cond) { __builtin_amdgcn_s_sleep(1); \
;     if ((++_sp & 255u) == 0u) { if (xb_ld(&(bar)[XB_TMO])) break; if (_sp > XB_SPIN_CAP) { atomicAdd(&(bar)[XB_TMO], 1u); break; } } } } while (0)
; __device__ __forceinline__ void xcd_barrier(const XcdBarrier& b) {
;     asm volatile("s_waitcnt vmcnt(0)" ::: "memory");
;     __syncthreads();
;     if (threadIdx.x == 0) {
;         unsigned* bar = b.bar;
;         __builtin_amdgcn_s_waitcnt(0);
;         unsigned nloc = b.st[0], nx = b.st[1];
;         if (nloc == 0u) { xcd_barrier_complete(bar, b.x, nloc, nx); b.st[0] = nloc; b.st[1] = nx; }
;         const unsigned old = xb_add(&bar[XB_XSUB(b.x)], 1u);
;         const unsigned gen = old / nloc;
;         if (old + 1u == (gen + 1u) * nloc) {
;             __builtin_amdgcn_fence(__ATOMIC_RELEASE, "agent");
;             asm volatile("s_waitcnt vmcnt(0)" ::: "memory");
;             const unsigned og = xb_add(&bar[XB_TOP], 1u);
;             const unsigned tg = og / nx;
;             if (og + 1u == (tg + 1u) * nx) xb_add(&bar[XB_TOPGEN], 1u);
;             else XB_SPIN(xb_ld(&bar[XB_TOPGEN]) == tg, bar);
;             __builtin_amdgcn_fence(__ATOMIC_ACQUIRE, "agent");
;             xb_add(&bar[XB_XGEN(b.x)], 1u);
;             asm volatile("s_waitcnt vmcnt(0)" ::: "memory");
;         } else {
;             XB_SPIN(xb_ld(&bar[XB_XGEN(b.x)]) == gen, bar);
;             __builtin_amdgcn_fence(__ATOMIC_ACQUIRE, "agent");
;             asm volatile("s_waitcnt vmcnt(0)" ::: "memory");
;         }
;     }
;     __syncthreads();
; }
.LBB0_615:
	s_or_b64 exec, exec, s[0:1]
	v_readfirstlane_b32 s101, v169
	s_nop 3
	s_lshr_b32 s101, s101, 6
	s_cmp_eq_u32 s101, 0
	s_cbranch_scc1 .Lcv_skip_D
	v_readlane_b32 s100, v255, 44
	s_nop 3
	s_mul_i32 s100, s100, 5
	s_add_i32 s100, s100, 4
	s_cmp_gt_u32 s100, 18
	s_cbranch_scc1 .Lcv_skip_D
	s_mul_i32 s100, s100, 2458
	s_add_i32 s100, s100, 3072
	s_add_i32 s99, s100, 2458
	s_min_i32 s99, s99, 0xc000
	s_sub_i32 s100, s100, s88
	s_mov_b32 s98, 7
	s_mov_b32 s101, 4
	v_readfirstlane_b32 s3, v169
	s_branch .Lcv_entry
